# scan: one static s_setprio 1 for waves 4-7 for the whole phase
# speedup vs baseline: 1.0046x; 1.0046x over previous
.LBB0_81:
	v_readfirstlane_b32 s98, v165
	s_lshr_b32 s98, s98, 8
	s_cmp_eq_u32 s98, 1
	s_cbranch_scc0 .Lscan_noprio
	s_setprio 1

.LBB0_96:
	s_setprio 0
	s_mov_b64 s[0:1], 0
